# even_d layer 0: the 48 third-round G3 items dealt by plain blockIdx (8 XCDs, 48 different CUs) instead of vblock<48 (one XCD)
# baseline (speedup 1.0000x reference)
; DI int vblock() { const int G = gridDim.x, b = blockIdx.x; return ((G & 7) == 0) ? (b & 7) * (G >> 3) + (b >> 3) : b; }
; DI void phase_even_d(const Ctx& c, int l, bf16* lds) {
;   const int n_ctx = (l == 0 ? 16 : 0), n_g3 = 8 * ((l == 0) ? 132 : 128);
;   for (int it = vblock(); it < n_ctx + n_g3; it += gridDim.x) {
;     if (it < n_ctx) attn_item(c, 512 + it, lds);
;     else gla_g3_item(c, l, it - n_ctx, lds);
;   }
; }
.LBB0_885:
	s_cmpk_lg_i32 s40, 0x200
	s_cbranch_scc1 .Led_std
	s_cmpk_lt_i32 s84, 0x200
	s_cbranch_scc1 .Led_std
	s_cmpk_ge_i32 s84, 0x400
	s_cbranch_scc1 .LBB0_1021
	v_readlane_b32 s0, v252, 32
	s_lshr_b32 s0, s0, 8
	s_add_i32 s84, s0, 0x400
	s_branch .Led_chk

; DI int vblock() { const int G = gridDim.x, b = blockIdx.x; return ((G & 7) == 0) ? (b & 7) * (G >> 3) + (b >> 3) : b; }
; DI void phase_even_d(const Ctx& c, int l, bf16* lds) {
;     ...
;   for (int it = vblock(); it < n_ctx + n_g3; it += gridDim.x) {
.Led_chk:
	v_readlane_b32 s0, v254, 59
	s_cmp_lt_i32 s84, s0
	s_cbranch_scc0 .LBB0_1021
